# P0 weight transposes: next-tile load wait moved from loop-body top to just before the register rotation
# baseline (speedup 1.0000x reference)
; DI u32 pk2(float a, float b) { f2_t v = {a, b}; bf2_t r = __builtin_convertvector(v, bf2_t); return __builtin_bit_cast(u32, r); }
; DI void transpose_w(const float* __restrict__ W, const float* __restrict__ gain, u16* __restrict__ Wt, int K, int Nsrc, int Nd, int gs, int gstride, int goff, float* tile) {
;     ...
;   const int r0 = tid >> 4, cq = (tid & 15) * 4;
;     ...
;   float4 c0v = make_float4(0.f, 0.f, 0.f, 0.f), c1v = c0v, n0v = c0v, n1v = c0v; float cg0 = 1.f, cg1 = 1.f, ng0 = 1.f, ng1 = 1.f;
;   int t = blockIdx.x;
;   if (t < total) TW_LOAD(t, c0v, c1v, cg0, cg1);
;   for (; t < total; t += G) {
;     const int kt = t % nkt, nt = t / nkt, n0 = nt * 64;
;     if (t + G < total) TW_LOAD(t + G, n0v, n1v, ng0, ng1);
;     {
;       float* tp = tile + r0 * 65 + cq;
;       tp[0] = c0v.x * cg0; tp[1] = c0v.y * cg0; tp[2] = c0v.z * cg0; tp[3] = c0v.w * cg0;
;       tp += 32 * 65;
;       tp[0] = c1v.x * cg1; tp[1] = c1v.y * cg1; tp[2] = c1v.z * cg1; tp[3] = c1v.w * cg1;
;     }
;     __syncthreads();
;     {
;       const int n = tid >> 3, k8 = tid & 7;
;       const float* tp = tile + (k8 * 8) * 65 + n;
;       u32x4 o;
;       o[0] = pk2(tp[0], tp[65]); o[1] = pk2(tp[130], tp[195]); o[2] = pk2(tp[260], tp[325]); o[3] = pk2(tp[390], tp[455]);
;       *(u32x4*)(Wt + (size_t)(n0 + n) * K + kt * 64 + k8 * 8) = o;
;     }
;     __syncthreads();
;     c0v = n0v; c1v = n1v; cg0 = ng0; cg1 = ng1;
;   }
.LBB0_7:
	v_ashrrev_i32_e32 v23, 3, v15
	v_lshlrev_b32_e32 v10, 3, v15
	s_movk_i32 s3, 0x104
	v_and_b32_e32 v16, 56, v10
	v_lshlrev_b32_e32 v10, 2, v23
	v_mad_u32_u24 v27, v16, s3, v10
	v_mov_b32_e32 v10, 0
	v_lshlrev_b32_e32 v17, 2, v1
	v_mul_lo_u32 v18, v14, s3
	s_lshl_b32 s10, s34, 6
	v_mov_b32_e32 v12, v10
	v_mov_b32_e32 v13, v10
	v_add_u32_e32 v32, s10, v14
	v_mov_b32_e32 v11, v10
	v_add_u32_e32 v33, v17, v18
	v_lshlrev_b32_e32 v24, 1, v16
	v_mov_b64_e32 v[16:17], v[12:13]
	v_mov_b64_e32 v[20:21], v[12:13]
	s_lshl_b32 s3, s2, 6
	v_mov_b32_e32 v30, 1.0
	s_movk_i32 s11, 0xc40
	s_movk_i32 s12, 0x3100
	v_add_u32_e32 v34, 0x2080, v33
	v_add_u32_e32 v35, 0x2088, v33
	v_mov_b32_e32 v25, v10
	v_add_u32_e32 v36, 0x400, v27
	v_mov_b64_e32 v[14:15], v[10:11]
	v_mov_b64_e32 v[18:19], v[10:11]
	v_mov_b32_e32 v11, 1.0
	s_mov_b32 s14, s33
	s_waitcnt vmcnt(0)
	s_branch .LBB0_9
.LBB0_8:
	s_nop 0
	v_pk_mul_f32 v[6:7], v[6:7], v[26:27] op_sel_hi:[1,0]
	v_pk_mul_f32 v[2:3], v[2:3], v[22:23] op_sel_hi:[1,0]
	ds_write2_b32 v33, v6, v7 offset1:1
	v_pk_mul_f32 v[6:7], v[8:9], v[26:27] op_sel_hi:[1,0]
	ds_write2_b32 v34, v2, v3 offset1:1
	v_pk_mul_f32 v[2:3], v[4:5], v[22:23] op_sel_hi:[1,0]
	s_ashr_i32 s8, s14, 31
	ds_write2_b32 v33, v6, v7 offset0:2 offset1:3
	ds_write2_b32 v35, v2, v3 offset1:1
	s_waitcnt lgkmcnt(0)
	s_barrier
	ds_read2_b32 v[2:3], v27 offset1:65
	ds_read2_b32 v[4:5], v27 offset0:130 offset1:195
	ds_read2_b32 v[6:7], v36 offset0:4 offset1:69
	ds_read2_b32 v[8:9], v36 offset0:134 offset1:199
	s_lshr_b32 s8, s8, 27
	s_add_i32 s8, s14, s8
	s_ashr_i32 s8, s8, 5
	s_waitcnt lgkmcnt(3)
	v_cvt_pk_bf16_f32 v2, v2, v3
	s_waitcnt lgkmcnt(2)
	v_cvt_pk_bf16_f32 v3, v4, v5
	s_waitcnt lgkmcnt(1)
	v_cvt_pk_bf16_f32 v4, v6, v7
	v_lshl_add_u32 v6, s8, 6, v23
	v_ashrrev_i32_e32 v7, 31, v6
	s_lshl_b32 s8, s8, 11
	v_lshlrev_b64 v[6:7], 12, v[6:7]
	s_sub_i32 s8, s3, s8
	v_lshl_add_u64 v[6:7], s[56:57], 0, v[6:7]
	s_ashr_i32 s9, s8, 31
	v_lshl_add_u64 v[6:7], s[8:9], 1, v[6:7]
	s_waitcnt lgkmcnt(0)
	v_cvt_pk_bf16_f32 v5, v8, v9
	v_lshl_add_u64 v[6:7], v[6:7], 0, v[24:25]
	global_store_dwordx4 v[6:7], v[2:5], off
	s_waitcnt vmcnt(1)
	v_mov_b64_e32 v[6:7], v[14:15]
	s_add_i32 s3, s3, s10
	v_mov_b64_e32 v[2:3], v[18:19]
	s_andn2_b64 vcc, exec, s[6:7]
	v_mov_b64_e32 v[8:9], v[16:17]
	v_mov_b64_e32 v[4:5], v[20:21]
	v_mov_b32_e32 v26, v30
	v_mov_b32_e32 v22, v11
	s_mov_b32 s14, s13
	s_barrier
	s_cbranch_vccz .LBB0_16

; DI u32 pk2(float a, float b) { f2_t v = {a, b}; bf2_t r = __builtin_convertvector(v, bf2_t); return __builtin_bit_cast(u32, r); }
; DI void transpose_w(const float* __restrict__ W, const float* __restrict__ gain, u16* __restrict__ Wt, int K, int Nsrc, int Nd, int gs, int gstride, int goff, float* tile) {
;     ...
;   const int r0 = tid >> 4, cq = (tid & 15) * 4;
;     ...
;   float4 c0v = make_float4(0.f, 0.f, 0.f, 0.f), c1v = c0v, n0v = c0v, n1v = c0v; float cg0 = 1.f, cg1 = 1.f, ng0 = 1.f, ng1 = 1.f;
;   int t = blockIdx.x;
;   if (t < total) TW_LOAD(t, c0v, c1v, cg0, cg1);
;   for (; t < total; t += G) {
;     const int kt = t % nkt, nt = t / nkt, n0 = nt * 64;
;     if (t + G < total) TW_LOAD(t + G, n0v, n1v, ng0, ng1);
;     {
;       float* tp = tile + r0 * 65 + cq;
;       tp[0] = c0v.x * cg0; tp[1] = c0v.y * cg0; tp[2] = c0v.z * cg0; tp[3] = c0v.w * cg0;
;       tp += 32 * 65;
;       tp[0] = c1v.x * cg1; tp[1] = c1v.y * cg1; tp[2] = c1v.z * cg1; tp[3] = c1v.w * cg1;
;     }
;     __syncthreads();
;     {
;       const int n = tid >> 3, k8 = tid & 7;
;       const float* tp = tile + (k8 * 8) * 65 + n;
;       u32x4 o;
;       o[0] = pk2(tp[0], tp[65]); o[1] = pk2(tp[130], tp[195]); o[2] = pk2(tp[260], tp[325]); o[3] = pk2(tp[390], tp[455]);
;       *(u32x4*)(Wt + (size_t)(n0 + n) * K + kt * 64 + k8 * 8) = o;
;     }
;     __syncthreads();
;     c0v = n0v; c1v = n1v; cg0 = ng0; cg1 = ng1;
;   }
.LBB0_21:
	v_ashrrev_i32_e32 v25, 3, v5
	v_lshlrev_b32_e32 v2, 3, v5
	s_movk_i32 s3, 0x104
	v_and_b32_e32 v14, 56, v2
	v_lshlrev_b32_e32 v2, 2, v25
	v_mad_u32_u24 v27, v14, s3, v2
	v_mov_b32_e32 v2, 0
	s_lshl_b32 s10, s34, 6
	v_lshlrev_b32_e32 v15, 2, v1
	v_mul_lo_u32 v16, v4, s3
	v_add_u32_e32 v32, s10, v4
	v_mov_b32_e32 v4, v2
	v_mov_b32_e32 v5, v2
	v_mov_b32_e32 v3, v2
	v_add_u32_e32 v33, v15, v16
	v_lshlrev_b32_e32 v22, 1, v14
	v_mov_b64_e32 v[16:17], v[4:5]
	v_mov_b64_e32 v[20:21], v[4:5]
	s_lshl_b32 s3, s2, 6
	v_mov_b32_e32 v30, 1.0
	s_movk_i32 s11, 0xc00
	s_movk_i32 s12, 0x3000
	v_add_u32_e32 v34, 0x2080, v33
	v_add_u32_e32 v35, 0x2088, v33
	v_mov_b32_e32 v23, v2
	v_add_u32_e32 v36, 0x400, v27
	v_mov_b64_e32 v[14:15], v[2:3]
	v_mov_b64_e32 v[18:19], v[2:3]
	v_mov_b32_e32 v3, 1.0
	s_mov_b32 s14, s33
	s_waitcnt vmcnt(0)
	s_branch .LBB0_23
.LBB0_22:
	s_nop 0
	v_pk_mul_f32 v[4:5], v[10:11], v[26:27] op_sel_hi:[1,0]
	ds_write2_b32 v33, v4, v5 offset1:1
	v_pk_mul_f32 v[4:5], v[12:13], v[26:27] op_sel_hi:[1,0]
	ds_write2_b32 v33, v4, v5 offset0:2 offset1:3
	v_pk_mul_f32 v[4:5], v[6:7], v[24:25] op_sel_hi:[1,0]
	ds_write2_b32 v34, v4, v5 offset1:1
	v_pk_mul_f32 v[4:5], v[8:9], v[24:25] op_sel_hi:[1,0]
	s_ashr_i32 s8, s14, 31
	ds_write2_b32 v35, v4, v5 offset1:1
	s_waitcnt lgkmcnt(0)
	s_barrier
	ds_read2_b32 v[4:5], v27 offset1:65
	ds_read2_b32 v[6:7], v27 offset0:130 offset1:195
	ds_read2_b32 v[8:9], v36 offset0:4 offset1:69
	ds_read2_b32 v[10:11], v36 offset0:134 offset1:199
	s_lshr_b32 s8, s8, 29
	s_add_i32 s8, s14, s8
	s_ashr_i32 s8, s8, 3
	s_waitcnt lgkmcnt(3)
	v_cvt_pk_bf16_f32 v4, v4, v5
	s_waitcnt lgkmcnt(2)
	v_cvt_pk_bf16_f32 v5, v6, v7
	s_waitcnt lgkmcnt(1)
	v_cvt_pk_bf16_f32 v6, v8, v9
	v_lshl_add_u32 v8, s8, 6, v25
	v_ashrrev_i32_e32 v9, 31, v8
	s_lshl_b32 s8, s8, 9
	v_lshlrev_b64 v[8:9], 10, v[8:9]
	s_sub_i32 s8, s3, s8
	v_lshl_add_u64 v[8:9], s[72:73], 0, v[8:9]
	s_ashr_i32 s9, s8, 31
	v_lshl_add_u64 v[8:9], s[8:9], 1, v[8:9]
	s_waitcnt lgkmcnt(0)
	v_cvt_pk_bf16_f32 v7, v10, v11
	v_lshl_add_u64 v[8:9], v[8:9], 0, v[22:23]
	global_store_dwordx4 v[8:9], v[4:7], off
	s_waitcnt vmcnt(1)
	v_mov_b64_e32 v[10:11], v[14:15]
	s_add_i32 s3, s3, s10
	v_mov_b64_e32 v[6:7], v[18:19]
	s_andn2_b64 vcc, exec, s[6:7]
	v_mov_b64_e32 v[12:13], v[16:17]
	v_mov_b64_e32 v[8:9], v[20:21]
	v_mov_b32_e32 v26, v30
	v_mov_b32_e32 v24, v3
	s_mov_b32 s14, s13
	s_barrier
	s_cbranch_vccz .LBB0_30

; DI u32 pk2(float a, float b) { f2_t v = {a, b}; bf2_t r = __builtin_convertvector(v, bf2_t); return __builtin_bit_cast(u32, r); }
; DI void transpose_w(const float* __restrict__ W, const float* __restrict__ gain, u16* __restrict__ Wt, int K, int Nsrc, int Nd, int gs, int gstride, int goff, float* tile) {
;     ...
;   const int r0 = tid >> 4, cq = (tid & 15) * 4;
;     ...
;   float4 c0v = make_float4(0.f, 0.f, 0.f, 0.f), c1v = c0v, n0v = c0v, n1v = c0v; float cg0 = 1.f, cg1 = 1.f, ng0 = 1.f, ng1 = 1.f;
;   int t = blockIdx.x;
;   if (t < total) TW_LOAD(t, c0v, c1v, cg0, cg1);
;   for (; t < total; t += G) {
;     const int kt = t % nkt, nt = t / nkt, n0 = nt * 64;
;     if (t + G < total) TW_LOAD(t + G, n0v, n1v, ng0, ng1);
;     {
;       float* tp = tile + r0 * 65 + cq;
;       tp[0] = c0v.x * cg0; tp[1] = c0v.y * cg0; tp[2] = c0v.z * cg0; tp[3] = c0v.w * cg0;
;       tp += 32 * 65;
;       tp[0] = c1v.x * cg1; tp[1] = c1v.y * cg1; tp[2] = c1v.z * cg1; tp[3] = c1v.w * cg1;
;     }
;     __syncthreads();
;     {
;       const int n = tid >> 3, k8 = tid & 7;
;       const float* tp = tile + (k8 * 8) * 65 + n;
;       u32x4 o;
;       o[0] = pk2(tp[0], tp[65]); o[1] = pk2(tp[130], tp[195]); o[2] = pk2(tp[260], tp[325]); o[3] = pk2(tp[390], tp[455]);
;       *(u32x4*)(Wt + (size_t)(n0 + n) * K + kt * 64 + k8 * 8) = o;
;     }
;     __syncthreads();
;     c0v = n0v; c1v = n1v; cg0 = ng0; cg1 = ng1;
;   }
.LBB0_37:
	v_ashrrev_i32_e32 v25, 3, v15
	v_lshlrev_b32_e32 v10, 3, v15
	s_movk_i32 s3, 0x104
	v_and_b32_e32 v16, 56, v10
	v_lshlrev_b32_e32 v10, 2, v25
	v_mad_u32_u24 v27, v16, s3, v10
	v_mov_b32_e32 v10, 0
	v_lshlrev_b32_e32 v17, 2, v1
	v_mul_lo_u32 v18, v14, s3
	s_lshl_b32 s12, s34, 6
	v_mov_b32_e32 v12, v10
	v_mov_b32_e32 v13, v10
	v_add_u32_e32 v32, s12, v14
	v_mov_b32_e32 v11, v10
	v_add_u32_e32 v33, v17, v18
	v_lshlrev_b32_e32 v22, 1, v16
	v_mov_b64_e32 v[16:17], v[12:13]
	v_mov_b64_e32 v[20:21], v[12:13]
	s_lshl_b32 s3, s2, 6
	v_mov_b32_e32 v30, 1.0
	s_movk_i32 s13, 0x1000
	v_add_u32_e32 v34, 0x2080, v33
	v_add_u32_e32 v35, 0x2088, v33
	v_mov_b32_e32 v23, v10
	v_add_u32_e32 v36, 0x400, v27
	v_mov_b64_e32 v[14:15], v[10:11]
	v_mov_b64_e32 v[18:19], v[10:11]
	v_mov_b32_e32 v11, 1.0
	s_mov_b32 s15, s33
	s_waitcnt vmcnt(0)
	s_branch .LBB0_39
.LBB0_38:
	s_nop 0
	v_pk_mul_f32 v[6:7], v[6:7], v[26:27] op_sel_hi:[1,0]
	v_pk_mul_f32 v[2:3], v[2:3], v[24:25] op_sel_hi:[1,0]
	ds_write2_b32 v33, v6, v7 offset1:1
	v_pk_mul_f32 v[6:7], v[8:9], v[26:27] op_sel_hi:[1,0]
	ds_write2_b32 v34, v2, v3 offset1:1
	v_pk_mul_f32 v[2:3], v[4:5], v[24:25] op_sel_hi:[1,0]
	s_ashr_i32 s10, s15, 31
	ds_write2_b32 v33, v6, v7 offset0:2 offset1:3
	ds_write2_b32 v35, v2, v3 offset1:1
	s_waitcnt lgkmcnt(0)
	s_barrier
	ds_read2_b32 v[2:3], v27 offset1:65
	ds_read2_b32 v[4:5], v27 offset0:130 offset1:195
	ds_read2_b32 v[6:7], v36 offset0:4 offset1:69
	ds_read2_b32 v[8:9], v36 offset0:134 offset1:199
	s_lshr_b32 s10, s10, 29
	s_add_i32 s10, s15, s10
	s_ashr_i32 s10, s10, 3
	s_waitcnt lgkmcnt(3)
	v_cvt_pk_bf16_f32 v2, v2, v3
	s_waitcnt lgkmcnt(2)
	v_cvt_pk_bf16_f32 v3, v4, v5
	s_waitcnt lgkmcnt(1)
	v_cvt_pk_bf16_f32 v4, v6, v7
	v_lshl_add_u32 v6, s10, 6, v25
	v_ashrrev_i32_e32 v7, 31, v6
	s_lshl_b32 s10, s10, 9
	v_lshlrev_b64 v[6:7], 10, v[6:7]
	s_sub_i32 s10, s3, s10
	v_lshl_add_u64 v[6:7], s[70:71], 0, v[6:7]
	s_ashr_i32 s11, s10, 31
	v_lshl_add_u64 v[6:7], s[10:11], 1, v[6:7]
	s_waitcnt lgkmcnt(0)
	v_cvt_pk_bf16_f32 v5, v8, v9
	v_lshl_add_u64 v[6:7], v[6:7], 0, v[22:23]
	global_store_dwordx4 v[6:7], v[2:5], off
	s_waitcnt vmcnt(1)
	v_mov_b64_e32 v[6:7], v[14:15]
	s_add_i32 s3, s3, s12
	v_mov_b64_e32 v[2:3], v[18:19]
	s_andn2_b64 vcc, exec, s[8:9]
	v_mov_b64_e32 v[8:9], v[16:17]
	v_mov_b64_e32 v[4:5], v[20:21]
	v_mov_b32_e32 v26, v30
	v_mov_b32_e32 v24, v11
	s_mov_b32 s15, s14
	s_barrier
	s_cbranch_vccz .LBB0_46

; DI u32 pk2(float a, float b) { f2_t v = {a, b}; bf2_t r = __builtin_convertvector(v, bf2_t); return __builtin_bit_cast(u32, r); }
; DI void transpose_w(const float* __restrict__ W, const float* __restrict__ gain, u16* __restrict__ Wt, int K, int Nsrc, int Nd, int gs, int gstride, int goff, float* tile) {
;     ...
;   const int r0 = tid >> 4, cq = (tid & 15) * 4;
;     ...
;   float4 c0v = make_float4(0.f, 0.f, 0.f, 0.f), c1v = c0v, n0v = c0v, n1v = c0v; float cg0 = 1.f, cg1 = 1.f, ng0 = 1.f, ng1 = 1.f;
;   int t = blockIdx.x;
;   if (t < total) TW_LOAD(t, c0v, c1v, cg0, cg1);
;   for (; t < total; t += G) {
;     const int kt = t % nkt, nt = t / nkt, n0 = nt * 64;
;     if (t + G < total) TW_LOAD(t + G, n0v, n1v, ng0, ng1);
;     {
;       float* tp = tile + r0 * 65 + cq;
;       tp[0] = c0v.x * cg0; tp[1] = c0v.y * cg0; tp[2] = c0v.z * cg0; tp[3] = c0v.w * cg0;
;       tp += 32 * 65;
;       tp[0] = c1v.x * cg1; tp[1] = c1v.y * cg1; tp[2] = c1v.z * cg1; tp[3] = c1v.w * cg1;
;     }
;     __syncthreads();
;     {
;       const int n = tid >> 3, k8 = tid & 7;
;       const float* tp = tile + (k8 * 8) * 65 + n;
;       u32x4 o;
;       o[0] = pk2(tp[0], tp[65]); o[1] = pk2(tp[130], tp[195]); o[2] = pk2(tp[260], tp[325]); o[3] = pk2(tp[390], tp[455]);
;       *(u32x4*)(Wt + (size_t)(n0 + n) * K + kt * 64 + k8 * 8) = o;
;     }
;     __syncthreads();
;     c0v = n0v; c1v = n1v; cg0 = ng0; cg1 = ng1;
;   }
.LBB0_53:
	v_ashrrev_i32_e32 v25, 3, v15
	v_lshlrev_b32_e32 v10, 3, v15
	v_lshlrev_b32_e32 v17, 2, v16
	s_movk_i32 s3, 0x104
	v_and_b32_e32 v16, 56, v10
	v_lshlrev_b32_e32 v10, 2, v25
	v_mad_u32_u24 v27, v16, s3, v10
	v_mov_b32_e32 v10, 0
	v_mul_lo_u32 v18, v14, s3
	s_lshl_b32 s10, s34, 6
	v_mov_b32_e32 v12, v10
	v_mov_b32_e32 v13, v10
	v_add_u32_e32 v32, s10, v14
	v_mov_b32_e32 v11, v10
	v_add_u32_e32 v33, v17, v18
	v_lshlrev_b32_e32 v22, 1, v16
	v_mov_b64_e32 v[16:17], v[12:13]
	v_mov_b64_e32 v[20:21], v[12:13]
	s_lshl_b32 s3, s2, 6
	v_mov_b32_e32 v30, 1.0
	s_movk_i32 s11, 0x1000
	v_add_u32_e32 v34, 0x2080, v33
	v_add_u32_e32 v35, 0x2088, v33
	v_mov_b32_e32 v23, v10
	v_add_u32_e32 v36, 0x400, v27
	v_mov_b64_e32 v[14:15], v[10:11]
	v_mov_b64_e32 v[18:19], v[10:11]
	v_mov_b32_e32 v11, 1.0
	s_mov_b32 s13, s33
	s_waitcnt vmcnt(0)
	s_branch .LBB0_55
.LBB0_54:
	s_nop 0
	v_pk_mul_f32 v[6:7], v[6:7], v[26:27] op_sel_hi:[1,0]
	v_pk_mul_f32 v[2:3], v[2:3], v[24:25] op_sel_hi:[1,0]
	ds_write2_b32 v33, v6, v7 offset1:1
	v_pk_mul_f32 v[6:7], v[8:9], v[26:27] op_sel_hi:[1,0]
	ds_write2_b32 v34, v2, v3 offset1:1
	v_pk_mul_f32 v[2:3], v[4:5], v[24:25] op_sel_hi:[1,0]
	s_ashr_i32 s8, s13, 31
	ds_write2_b32 v33, v6, v7 offset0:2 offset1:3
	ds_write2_b32 v35, v2, v3 offset1:1
	s_waitcnt lgkmcnt(0)
	s_barrier
	ds_read2_b32 v[2:3], v27 offset1:65
	ds_read2_b32 v[4:5], v27 offset0:130 offset1:195
	ds_read2_b32 v[6:7], v36 offset0:4 offset1:69
	ds_read2_b32 v[8:9], v36 offset0:134 offset1:199
	s_lshr_b32 s8, s8, 29
	s_add_i32 s8, s13, s8
	s_ashr_i32 s8, s8, 3
	s_waitcnt lgkmcnt(3)
	v_cvt_pk_bf16_f32 v2, v2, v3
	s_waitcnt lgkmcnt(2)
	v_cvt_pk_bf16_f32 v3, v4, v5
	s_waitcnt lgkmcnt(1)
	v_cvt_pk_bf16_f32 v4, v6, v7
	v_lshl_add_u32 v6, s8, 6, v25
	v_ashrrev_i32_e32 v7, 31, v6
	s_lshl_b32 s8, s8, 9
	v_lshlrev_b64 v[6:7], 10, v[6:7]
	s_sub_i32 s8, s3, s8
	v_lshl_add_u64 v[6:7], s[68:69], 0, v[6:7]
	s_ashr_i32 s9, s8, 31
	v_lshl_add_u64 v[6:7], s[8:9], 1, v[6:7]
	s_waitcnt lgkmcnt(0)
	v_cvt_pk_bf16_f32 v5, v8, v9
	v_lshl_add_u64 v[6:7], v[6:7], 0, v[22:23]
	global_store_dwordx4 v[6:7], v[2:5], off
	s_waitcnt vmcnt(1)
	v_mov_b64_e32 v[6:7], v[14:15]
	s_add_i32 s3, s3, s10
	v_mov_b64_e32 v[2:3], v[18:19]
	s_andn2_b64 vcc, exec, s[6:7]
	v_mov_b64_e32 v[8:9], v[16:17]
	v_mov_b64_e32 v[4:5], v[20:21]
	v_mov_b32_e32 v26, v30
	v_mov_b32_e32 v24, v11
	s_mov_b32 s13, s12
	s_barrier
	s_cbranch_vccz .LBB0_62

; DI u32 pk2(float a, float b) { f2_t v = {a, b}; bf2_t r = __builtin_convertvector(v, bf2_t); return __builtin_bit_cast(u32, r); }
; DI void transpose_w(const float* __restrict__ W, const float* __restrict__ gain, u16* __restrict__ Wt, int K, int Nsrc, int Nd, int gs, int gstride, int goff, float* tile) {
;     ...
;   const int r0 = tid >> 4, cq = (tid & 15) * 4;
;     ...
;   float4 c0v = make_float4(0.f, 0.f, 0.f, 0.f), c1v = c0v, n0v = c0v, n1v = c0v; float cg0 = 1.f, cg1 = 1.f, ng0 = 1.f, ng1 = 1.f;
;   int t = blockIdx.x;
;   if (t < total) TW_LOAD(t, c0v, c1v, cg0, cg1);
;   for (; t < total; t += G) {
;     const int kt = t % nkt, nt = t / nkt, n0 = nt * 64;
;     if (t + G < total) TW_LOAD(t + G, n0v, n1v, ng0, ng1);
;     {
;       float* tp = tile + r0 * 65 + cq;
;       tp[0] = c0v.x * cg0; tp[1] = c0v.y * cg0; tp[2] = c0v.z * cg0; tp[3] = c0v.w * cg0;
;       tp += 32 * 65;
;       tp[0] = c1v.x * cg1; tp[1] = c1v.y * cg1; tp[2] = c1v.z * cg1; tp[3] = c1v.w * cg1;
;     }
;     __syncthreads();
;     {
;       const int n = tid >> 3, k8 = tid & 7;
;       const float* tp = tile + (k8 * 8) * 65 + n;
;       u32x4 o;
;       o[0] = pk2(tp[0], tp[65]); o[1] = pk2(tp[130], tp[195]); o[2] = pk2(tp[260], tp[325]); o[3] = pk2(tp[390], tp[455]);
;       *(u32x4*)(Wt + (size_t)(n0 + n) * K + kt * 64 + k8 * 8) = o;
;     }
;     __syncthreads();
;     c0v = n0v; c1v = n1v; cg0 = ng0; cg1 = ng1;
;   }
.LBB0_74:
	v_ashrrev_i32_e32 v25, 3, v5
	v_lshlrev_b32_e32 v2, 3, v5
	s_movk_i32 s3, 0x104
	v_and_b32_e32 v14, 56, v2
	v_lshlrev_b32_e32 v2, 2, v25
	v_mad_u32_u24 v27, v14, s3, v2
	v_mov_b32_e32 v2, 0
	s_lshl_b32 s12, s34, 6
	v_lshlrev_b32_e32 v15, 2, v1
	v_mul_lo_u32 v16, v4, s3
	v_add_u32_e32 v32, s12, v4
	v_mov_b32_e32 v4, v2
	v_mov_b32_e32 v5, v2
	v_mov_b32_e32 v3, v2
	v_add_u32_e32 v33, v15, v16
	v_lshlrev_b32_e32 v22, 1, v14
	v_mov_b64_e32 v[16:17], v[4:5]
	v_mov_b64_e32 v[20:21], v[4:5]
	s_lshl_b32 s3, s2, 6
	v_mov_b32_e32 v30, 1.0
	s_movk_i32 s13, 0x2000
	v_add_u32_e32 v34, 0x2080, v33
	v_add_u32_e32 v35, 0x2088, v33
	v_mov_b32_e32 v23, v2
	v_add_u32_e32 v36, 0x400, v27
	v_mov_b64_e32 v[14:15], v[2:3]
	v_mov_b64_e32 v[18:19], v[2:3]
	v_mov_b32_e32 v3, 1.0
	s_mov_b32 s15, s33
	s_waitcnt vmcnt(0)
	s_branch .LBB0_76
.LBB0_75:
	s_nop 0
	v_pk_mul_f32 v[4:5], v[10:11], v[26:27] op_sel_hi:[1,0]
	ds_write2_b32 v33, v4, v5 offset1:1
	v_pk_mul_f32 v[4:5], v[12:13], v[26:27] op_sel_hi:[1,0]
	ds_write2_b32 v33, v4, v5 offset0:2 offset1:3
	v_pk_mul_f32 v[4:5], v[6:7], v[24:25] op_sel_hi:[1,0]
	ds_write2_b32 v34, v4, v5 offset1:1
	v_pk_mul_f32 v[4:5], v[8:9], v[24:25] op_sel_hi:[1,0]
	s_ashr_i32 s10, s15, 31
	ds_write2_b32 v35, v4, v5 offset1:1
	s_waitcnt lgkmcnt(0)
	s_barrier
	ds_read2_b32 v[4:5], v27 offset1:65
	ds_read2_b32 v[6:7], v27 offset0:130 offset1:195
	ds_read2_b32 v[8:9], v36 offset0:4 offset1:69
	ds_read2_b32 v[10:11], v36 offset0:134 offset1:199
	s_lshr_b32 s10, s10, 27
	s_add_i32 s10, s15, s10
	s_ashr_i32 s10, s10, 5
	s_waitcnt lgkmcnt(3)
	v_cvt_pk_bf16_f32 v4, v4, v5
	s_waitcnt lgkmcnt(2)
	v_cvt_pk_bf16_f32 v5, v6, v7
	s_waitcnt lgkmcnt(1)
	v_cvt_pk_bf16_f32 v6, v8, v9
	v_lshl_add_u32 v8, s10, 6, v25
	v_ashrrev_i32_e32 v9, 31, v8
	s_lshl_b32 s10, s10, 11
	v_lshlrev_b64 v[8:9], 12, v[8:9]
	s_sub_i32 s10, s3, s10
	v_lshl_add_u64 v[8:9], s[64:65], 0, v[8:9]
	s_ashr_i32 s11, s10, 31
	v_lshl_add_u64 v[8:9], s[10:11], 1, v[8:9]
	s_waitcnt lgkmcnt(0)
	v_cvt_pk_bf16_f32 v7, v10, v11
	v_lshl_add_u64 v[8:9], v[8:9], 0, v[22:23]
	global_store_dwordx4 v[8:9], v[4:7], off
	s_waitcnt vmcnt(1)
	v_mov_b64_e32 v[10:11], v[14:15]
	s_add_i32 s3, s3, s12
	v_mov_b64_e32 v[6:7], v[18:19]
	s_andn2_b64 vcc, exec, s[6:7]
	v_mov_b64_e32 v[12:13], v[16:17]
	v_mov_b64_e32 v[8:9], v[20:21]
	v_mov_b32_e32 v26, v30
	v_mov_b32_e32 v24, v3
	s_mov_b32 s15, s14
	s_barrier
	s_cbranch_vccz .LBB0_83

; DI u32 pk2(float a, float b) { f2_t v = {a, b}; bf2_t r = __builtin_convertvector(v, bf2_t); return __builtin_bit_cast(u32, r); }
; DI void transpose_w(const float* __restrict__ W, const float* __restrict__ gain, u16* __restrict__ Wt, int K, int Nsrc, int Nd, int gs, int gstride, int goff, float* tile) {
;     ...
;   const int r0 = tid >> 4, cq = (tid & 15) * 4;
;     ...
;   float4 c0v = make_float4(0.f, 0.f, 0.f, 0.f), c1v = c0v, n0v = c0v, n1v = c0v; float cg0 = 1.f, cg1 = 1.f, ng0 = 1.f, ng1 = 1.f;
;   int t = blockIdx.x;
;   if (t < total) TW_LOAD(t, c0v, c1v, cg0, cg1);
;   for (; t < total; t += G) {
;     const int kt = t % nkt, nt = t / nkt, n0 = nt * 64;
;     if (t + G < total) TW_LOAD(t + G, n0v, n1v, ng0, ng1);
;     {
;       float* tp = tile + r0 * 65 + cq;
;       tp[0] = c0v.x * cg0; tp[1] = c0v.y * cg0; tp[2] = c0v.z * cg0; tp[3] = c0v.w * cg0;
;       tp += 32 * 65;
;       tp[0] = c1v.x * cg1; tp[1] = c1v.y * cg1; tp[2] = c1v.z * cg1; tp[3] = c1v.w * cg1;
;     }
;     __syncthreads();
;     {
;       const int n = tid >> 3, k8 = tid & 7;
;       const float* tp = tile + (k8 * 8) * 65 + n;
;       u32x4 o;
;       o[0] = pk2(tp[0], tp[65]); o[1] = pk2(tp[130], tp[195]); o[2] = pk2(tp[260], tp[325]); o[3] = pk2(tp[390], tp[455]);
;       *(u32x4*)(Wt + (size_t)(n0 + n) * K + kt * 64 + k8 * 8) = o;
;     }
;     __syncthreads();
;     c0v = n0v; c1v = n1v; cg0 = ng0; cg1 = ng1;
;   }
.LBB0_88:
	s_movk_i32 s3, 0x104
	v_ashrrev_i32_e32 v25, 3, v5
	v_lshlrev_b32_e32 v2, 3, v5
	v_mov_b32_e32 v3, 0
	s_lshl_b32 s6, s34, 6
	v_lshlrev_b32_e32 v15, 2, v14
	v_mul_lo_u32 v16, v4, s3
	v_and_b32_e32 v14, 56, v2
	v_lshlrev_b32_e32 v2, 2, v25
	v_add_u32_e32 v28, s6, v4
	v_mov_b32_e32 v4, v3
	v_mov_b32_e32 v5, v3
	v_mad_u32_u24 v27, v14, s3, v2
	v_mov_b32_e32 v2, v3
	v_add_u32_e32 v29, v15, v16
	v_lshlrev_b32_e32 v22, 1, v14
	v_mov_b64_e32 v[16:17], v[4:5]
	v_mov_b64_e32 v[20:21], v[4:5]
	s_lshl_b32 s3, s2, 6
	v_mov_b32_e32 v33, 1.0
	v_add_u32_e32 v30, 0x2080, v29
	v_add_u32_e32 v31, 0x2088, v29
	v_mov_b32_e32 v23, v3
	v_add_u32_e32 v32, 0x400, v27
	v_mov_b64_e32 v[14:15], v[2:3]
	v_mov_b64_e32 v[18:19], v[2:3]
	v_mov_b32_e32 v2, 1.0
	s_mov_b32 s8, s33
	s_waitcnt vmcnt(0)
	s_branch .LBB0_90
.LBB0_89:
	s_nop 0
	v_pk_mul_f32 v[4:5], v[10:11], v[26:27] op_sel_hi:[1,0]
	ds_write2_b32 v29, v4, v5 offset1:1
	v_pk_mul_f32 v[4:5], v[12:13], v[26:27] op_sel_hi:[1,0]
	ds_write2_b32 v29, v4, v5 offset0:2 offset1:3
	v_pk_mul_f32 v[4:5], v[6:7], v[24:25] op_sel_hi:[1,0]
	ds_write2_b32 v30, v4, v5 offset1:1
	v_pk_mul_f32 v[4:5], v[8:9], v[24:25] op_sel_hi:[1,0]
	s_ashr_i32 s9, s8, 31
	ds_write2_b32 v31, v4, v5 offset1:1
	s_waitcnt lgkmcnt(0)
	s_barrier
	ds_read2_b32 v[4:5], v27 offset1:65
	ds_read2_b32 v[6:7], v27 offset0:130 offset1:195
	ds_read2_b32 v[8:9], v32 offset0:4 offset1:69
	ds_read2_b32 v[10:11], v32 offset0:134 offset1:199
	s_lshr_b32 s9, s9, 27
	s_add_i32 s8, s8, s9
	s_ashr_i32 s8, s8, 5
	s_waitcnt lgkmcnt(3)
	v_cvt_pk_bf16_f32 v4, v4, v5
	s_waitcnt lgkmcnt(2)
	v_cvt_pk_bf16_f32 v5, v6, v7
	s_waitcnt lgkmcnt(1)
	v_cvt_pk_bf16_f32 v6, v8, v9
	v_lshl_add_u32 v8, s8, 6, v25
	v_ashrrev_i32_e32 v9, 31, v8
	s_lshl_b32 s8, s8, 11
	v_lshlrev_b64 v[8:9], 12, v[8:9]
	s_sub_i32 s8, s3, s8
	v_lshl_add_u64 v[8:9], s[20:21], 0, v[8:9]
	s_ashr_i32 s9, s8, 31
	v_lshl_add_u64 v[8:9], s[8:9], 1, v[8:9]
	s_waitcnt lgkmcnt(0)
	v_cvt_pk_bf16_f32 v7, v10, v11
	v_lshl_add_u64 v[8:9], v[8:9], 0, v[22:23]
	global_store_dwordx4 v[8:9], v[4:7], off
	s_waitcnt vmcnt(1)
	v_mov_b64_e32 v[10:11], v[14:15]
	s_add_i32 s3, s3, s6
	v_mov_b64_e32 v[6:7], v[18:19]
	s_andn2_b64 vcc, exec, s[4:5]
	v_mov_b64_e32 v[12:13], v[16:17]
	v_mov_b64_e32 v[8:9], v[20:21]
	v_mov_b32_e32 v26, v33
	v_mov_b32_e32 v24, v2
	s_mov_b32 s8, s7
	s_barrier
	s_cbranch_vccz .LBB0_95

; DI u32 pk2(float a, float b) { f2_t v = {a, b}; bf2_t r = __builtin_convertvector(v, bf2_t); return __builtin_bit_cast(u32, r); }
; DI void transpose_w(const float* __restrict__ W, const float* __restrict__ gain, u16* __restrict__ Wt, int K, int Nsrc, int Nd, int gs, int gstride, int goff, float* tile) {
;     ...
;   for (; t < total; t += G) {
;     const int kt = t % nkt, nt = t / nkt, n0 = nt * 64;
;     if (t + G < total) TW_LOAD(t + G, n0v, n1v, ng0, ng1);
;     {
;       float* tp = tile + r0 * 65 + cq;
;       tp[0] = c0v.x * cg0; tp[1] = c0v.y * cg0; tp[2] = c0v.z * cg0; tp[3] = c0v.w * cg0;
;       tp += 32 * 65;
;       tp[0] = c1v.x * cg1; tp[1] = c1v.y * cg1; tp[2] = c1v.z * cg1; tp[3] = c1v.w * cg1;
;     }
;     __syncthreads();
;     {
;       const int n = tid >> 3, k8 = tid & 7;
;       const float* tp = tile + (k8 * 8) * 65 + n;
;       u32x4 o;
;       o[0] = pk2(tp[0], tp[65]); o[1] = pk2(tp[130], tp[195]); o[2] = pk2(tp[260], tp[325]); o[3] = pk2(tp[390], tp[455]);
;       *(u32x4*)(Wt + (size_t)(n0 + n) * K + kt * 64 + k8 * 8) = o;
;     }
;     __syncthreads();
;     c0v = n0v; c1v = n1v; cg0 = ng0; cg1 = ng1;
;   }
.LBB0_101:
	s_nop 0
	v_pk_mul_f32 v[4:5], v[10:11], v[26:27] op_sel_hi:[1,0]
	ds_write2_b32 v29, v4, v5 offset1:1
	v_pk_mul_f32 v[4:5], v[12:13], v[26:27] op_sel_hi:[1,0]
	ds_write2_b32 v29, v4, v5 offset0:2 offset1:3
	v_pk_mul_f32 v[4:5], v[6:7], v[24:25] op_sel_hi:[1,0]
	ds_write2_b32 v30, v4, v5 offset1:1
	v_pk_mul_f32 v[4:5], v[8:9], v[24:25] op_sel_hi:[1,0]
	s_ashr_i32 s9, s8, 31
	ds_write2_b32 v31, v4, v5 offset1:1
	s_waitcnt lgkmcnt(0)
	s_barrier
	ds_read2_b32 v[4:5], v27 offset1:65
	ds_read2_b32 v[6:7], v27 offset0:130 offset1:195
	ds_read2_b32 v[8:9], v32 offset0:4 offset1:69
	ds_read2_b32 v[10:11], v32 offset0:134 offset1:199
	s_lshr_b32 s9, s9, 27
	s_add_i32 s8, s8, s9
	s_ashr_i32 s8, s8, 5
	s_waitcnt lgkmcnt(3)
	v_cvt_pk_bf16_f32 v4, v4, v5
	s_waitcnt lgkmcnt(2)
	v_cvt_pk_bf16_f32 v5, v6, v7
	s_waitcnt lgkmcnt(1)
	v_cvt_pk_bf16_f32 v6, v8, v9
	v_lshl_add_u32 v8, s8, 6, v25
	v_ashrrev_i32_e32 v9, 31, v8
	s_lshl_b32 s8, s8, 11
	v_lshlrev_b64 v[8:9], 12, v[8:9]
	s_sub_i32 s8, s3, s8
	v_lshl_add_u64 v[8:9], s[60:61], 0, v[8:9]
	s_ashr_i32 s9, s8, 31
	v_lshl_add_u64 v[8:9], s[8:9], 1, v[8:9]
	s_waitcnt lgkmcnt(0)
	v_cvt_pk_bf16_f32 v7, v10, v11
	v_lshl_add_u64 v[8:9], v[8:9], 0, v[22:23]
	global_store_dwordx4 v[8:9], v[4:7], off
	s_waitcnt vmcnt(1)
	v_mov_b64_e32 v[10:11], v[14:15]
	s_add_i32 s3, s3, s6
	v_mov_b64_e32 v[6:7], v[18:19]
	s_andn2_b64 vcc, exec, s[4:5]
	v_mov_b64_e32 v[12:13], v[16:17]
	v_mov_b64_e32 v[8:9], v[20:21]
	v_mov_b32_e32 v26, v33
	v_mov_b32_e32 v24, v2
	s_mov_b32 s8, s7
	s_barrier
	s_cbranch_vccz .LBB0_107
